# layer-0 pool/proj/w_out weight conversion moved from phase 0 into the tail of layer 0's first GEMM; P5 hand-off write-back fence dropped
# baseline (speedup 1.0000x reference)
; __device__ __forceinline__ void run_phase(const Params& p, int ph, LAS unsigned char* lds, const int tid, const int bid) {
;     const int G = gridDim.x;
;     if (ph == 0) { if (PH_MASK & 1) phase0(p, lds, tid, bid); return; }
;     if (ph == 13) { if (PH_MASK & 128) for (int it = bid; it < MR / 16; it += G) final_item(p, it, tid); return; }
;     const int l = (ph - 1) / 6, sub = (ph - 1) % 6;
;     if (sub == 0) { if (PH_MASK & 2) {
;         SchedPlain S; S.init(MPAD, NIN, G, bid); S.A = pws(p) + OFF_XB; S.Bt = pws(p) + OFF_WIN + l * SZ_WIN; S.tstepA = (size_t)256 * D * 2; S.tstepB = (size_t)256 * D * 2;
;         EpiWin E; E.u = (float*)(pws(p) + OFF_U); E.zb = (bf16_t*)(pws(p) + OFF_ZB); E.rsq = (const float*)(pws(p) + OFF_RSQ) + (size_t)l * MPAD; E.cf = (const float*)(pws(p) + OFF_CS);
;         gemm_phase(lds, S, E, D, D, D, tid); }
;     } else if (sub == 1) { if (PH_MASK & 4)
;         for (int it = bid; it < 1024 + 544 + 580; it += G) {
;             if (it < 1024) sample_ret_unit(p, l, it, lds, tid);
;             else if (it < 1568) kv_unit(p, it - 1024, lds, tid);
;             else pool_item(p, l, it - 1568, tid);
;         }
;     } else if (sub == 2) { if (PH_MASK & 8) {
;         for (int it = bid; it + G < 1024; it += 2 * G) scan_item2(p, l, it, it + G, tid); }
;     } else if (sub == 3) { if (PH_MASK & 16) {
;         SchedPool S; S.init(MPAD, D, G, (bid + 128) % G); S.A = pws(p) + OFF_POOLED; S.Bt = pws(p) + OFF_WPOOL + l * SZ_WPOOL;
;         EpiPool E; E.ain = (bf16_t*)(pws(p) + OFF_AIN); E.zb = (const bf16_t*)(pws(p) + OFF_ZB);
;         gemm_phase(lds, S, E, 512, D, 512, tid);
;         for (int it = bid; it < 544; it += G) ret_out_unit(p, l, it, lds, launder(tid)); }
;     } else if (sub == 4) { if (PH_MASK & 32) {
;         SchedDual S; S.init(MPAD, D, G, bid); S.A = pws(p) + OFF_AIN; S.Bt = pws(p) + OFF_WPR + l * SZ_WPR;
;         EpiDual E; E.merged = (bf16_t*)(pws(p) + OFF_MERGED); E.zb = (const bf16_t*)(pws(p) + OFF_ZB);
;         { const int sidx = bid < 40 ? bid : (bid < 80 ? bid - 40 : 0); E.m1 = (float*)(pws(p) + OFF_M1) + ((size_t)l * 40 + sidx) * 65536; E.flag = (unsigned*)(pws(p) + OFF_BAR + 16384) + (l * 40 + sidx) * 64; }
;         gemm_phase(lds, S, E, D, D, D, tid);
;         if (l == 0 && bid >= 80) for (int it = bid - 80; it < 1440; it += G - 80) conv_item(p, 1, it, lds, launder(tid)); }
.LBB0_5:
	s_or_b64 exec, exec, s[0:1]
	s_load_dwordx4 s[84:87], s[88:89], 0x68
	s_load_dwordx2 s[6:7], s[88:89], 0x78
	s_load_dwordx16 s[44:59], s[88:89], 0x0
	s_load_dwordx4 s[8:11], s[88:89], 0x40
	s_mul_i32 s0, s43, s42
	v_mov_b32_e32 v234, 0x3ecc95a3
	v_mov_b32_e32 v190, 0x358637bd
	s_waitcnt lgkmcnt(0)
	s_add_u32 s66, s86, 0x4000000
	s_addc_u32 s67, s87, 0
	s_add_u32 s76, s6, 0xb400000
	s_addc_u32 s77, s7, 0
	s_add_u32 s4, s84, 0x1000
	s_addc_u32 s5, s85, 0
	s_add_u32 s2, s84, 0x1400
	s_addc_u32 s3, s85, 0
	s_add_u32 s72, s84, 0x1800
	s_addc_u32 s73, s85, 0
	s_add_u32 s94, s84, 0x1c00
	s_addc_u32 s95, s85, 0
	s_add_u32 s12, s6, 0x41b28000
	s_addc_u32 s13, s7, 0
	s_add_u32 s68, s6, 0xfe00000
	v_writelane_b32 v253, s12, 5
	s_addc_u32 s69, s7, 0
	v_mov_b32_e32 v235, 0x2000
	v_writelane_b32 v253, s13, 6
	s_add_u32 s12, s6, 0x12300000
	s_addc_u32 s13, s7, 0
	v_writelane_b32 v253, s12, 7
	s_add_u32 s1, s6, 0x8000000
	v_mov_b32_e32 v236, 1
	v_writelane_b32 v253, s13, 8
	v_writelane_b32 v253, s1, 9
	s_addc_u32 s1, s7, 0
	s_cmp_lg_u64 s[8:9], 0
	v_writelane_b32 v253, s1, 10
	s_cselect_b64 s[12:13], -1, 0
	v_writelane_b32 v253, s12, 11
	s_cmp_lg_u64 s[54:55], 0
	v_mov_b64_e32 v[246:247], 0x127
	v_writelane_b32 v253, s13, 12
	s_cselect_b64 s[12:13], -1, 0
	s_add_u32 s96, s6, 0x29628000
	v_writelane_b32 v253, s12, 13
	s_addc_u32 s97, s7, 0
	s_add_u32 s1, s6, 0x8400000
	v_writelane_b32 v253, s13, 14
	v_writelane_b32 v253, s1, 15
	s_addc_u32 s1, s7, 0
	s_add_u32 s12, s6, 0x32a28000
	v_writelane_b32 v253, s1, 16
	s_addc_u32 s13, s7, 0
	v_writelane_b32 v253, s12, 17
	v_mov_b64_e32 v[248:249], 0x128
	v_mov_b32_e32 v237, 0x42800000
	v_writelane_b32 v253, s13, 18
	s_add_u32 s12, s6, 0x16e28000
	s_addc_u32 s13, s7, 0
	v_writelane_b32 v253, s12, 19
	s_add_u32 s1, s6, 0x2e028000
	v_mov_b32_e32 v238, 0x7fc00000
	v_writelane_b32 v253, s13, 20
	v_writelane_b32 v253, s1, 21
	s_addc_u32 s1, s7, 0
	v_writelane_b32 v253, s1, 22
	s_add_u32 s1, s6, 0x41d32000
	v_writelane_b32 v253, s1, 23
	s_addc_u32 s1, s7, 0
	v_writelane_b32 v253, s1, 24
	s_ashr_i32 s1, s42, 31
	v_writelane_b32 v253, s1, 25
	s_add_i32 s1, s42, 0xffffffb0
	v_writelane_b32 v253, s1, 26
	s_add_u32 s1, s56, 0x8000000
	v_writelane_b32 v253, s1, 27
	s_addc_u32 s1, s57, 0
	v_writelane_b32 v253, s1, 28
	s_add_u32 s1, s6, 0x4000000
	v_writelane_b32 v253, s1, 29
	s_addc_u32 s1, s7, 0
	v_writelane_b32 v253, s1, 30
	s_load_dword s1, s[88:89], 0x90
	v_mov_b32_e32 v239, 0xff800000
	v_not_b32_e32 v240, 63
	v_mov_b32_e32 v196, 0x3f317218
	v_mov_b32_e32 v241, 0x1e000
	s_waitcnt lgkmcnt(0)
; __device__ __forceinline__ void run_phase(const Params& p, int ph, LAS unsigned char* lds, const int tid, const int bid) {
;     const int G = gridDim.x;
;     if (ph == 0) { if (PH_MASK & 1) phase0(p, lds, tid, bid); return; }
;     if (ph == 13) { if (PH_MASK & 128) for (int it = bid; it < MR / 16; it += G) final_item(p, it, tid); return; }
;     const int l = (ph - 1) / 6, sub = (ph - 1) % 6;
;     if (sub == 0) { if (PH_MASK & 2) {
;         SchedPlain S; S.init(MPAD, NIN, G, bid); S.A = pws(p) + OFF_XB; S.Bt = pws(p) + OFF_WIN + l * SZ_WIN; S.tstepA = (size_t)256 * D * 2; S.tstepB = (size_t)256 * D * 2;
;         EpiWin E; E.u = (float*)(pws(p) + OFF_U); E.zb = (bf16_t*)(pws(p) + OFF_ZB); E.rsq = (const float*)(pws(p) + OFF_RSQ) + (size_t)l * MPAD; E.cf = (const float*)(pws(p) + OFF_CS);
;         gemm_phase(lds, S, E, D, D, D, tid); }
;     } else if (sub == 1) { if (PH_MASK & 4)
;         for (int it = bid; it < 1024 + 544 + 580; it += G) {
;             if (it < 1024) sample_ret_unit(p, l, it, lds, tid);
;             else if (it < 1568) kv_unit(p, it - 1024, lds, tid);
;             else pool_item(p, l, it - 1568, tid);
;         }
;     } else if (sub == 2) { if (PH_MASK & 8) {
;         for (int it = bid; it + G < 1024; it += 2 * G) scan_item2(p, l, it, it + G, tid); }
;     } else if (sub == 3) { if (PH_MASK & 16) {
;         SchedPool S; S.init(MPAD, D, G, (bid + 128) % G); S.A = pws(p) + OFF_POOLED; S.Bt = pws(p) + OFF_WPOOL + l * SZ_WPOOL;
;         EpiPool E; E.ain = (bf16_t*)(pws(p) + OFF_AIN); E.zb = (const bf16_t*)(pws(p) + OFF_ZB);
;         gemm_phase(lds, S, E, 512, D, 512, tid);
;         for (int it = bid; it < 544; it += G) ret_out_unit(p, l, it, lds, launder(tid)); }
;     } else if (sub == 4) { if (PH_MASK & 32) {
;         SchedDual S; S.init(MPAD, D, G, bid); S.A = pws(p) + OFF_AIN; S.Bt = pws(p) + OFF_WPR + l * SZ_WPR;
;         EpiDual E; E.merged = (bf16_t*)(pws(p) + OFF_MERGED); E.zb = (const bf16_t*)(pws(p) + OFF_ZB);
;         { const int sidx = bid < 40 ? bid : (bid < 80 ? bid - 40 : 0); E.m1 = (float*)(pws(p) + OFF_M1) + ((size_t)l * 40 + sidx) * 65536; E.flag = (unsigned*)(pws(p) + OFF_BAR + 16384) + (l * 40 + sidx) * 64; }
;         gemm_phase(lds, S, E, D, D, D, tid);
;         if (l == 0 && bid >= 80) for (int it = bid - 80; it < 1440; it += G - 80) conv_item(p, 1, it, lds, launder(tid)); }
	s_mul_i32 s0, s0, s1
	v_writelane_b32 v253, s0, 31
	s_add_u32 s0, s54, 0x2000
	s_addc_u32 s1, s55, 0
	v_writelane_b32 v253, s0, 32
	v_mov_b32_e32 v242, 0x37000000
	v_mov_b32_e32 v243, 0x7f800000
	v_writelane_b32 v253, s1, 33
	s_add_u32 s0, s6, 0x27128000
	s_addc_u32 s1, s7, 0
	v_writelane_b32 v253, s0, 34
	s_mov_b32 s78, 0x800000
	s_movk_i32 s74, 0x7000
	v_writelane_b32 v253, s1, 35
	s_add_u32 s0, s6, 0x3d728000
	s_addc_u32 s1, s7, 0
	s_lshl_b32 s60, s42, 1
	s_add_u32 s41, s6, 0x34f28000
	s_addc_u32 s40, s7, 0
	v_writelane_b32 v253, s1, 36
	s_add_u32 s1, s86, 0x48f0000
	v_writelane_b32 v253, s1, 37
	s_addc_u32 s1, s87, 0
	s_add_u32 s12, s6, 0x12428000
	v_writelane_b32 v253, s1, 38
	s_addc_u32 s13, s7, 0
	v_writelane_b32 v253, s12, 39
	s_mov_b32 s75, 0xc2fc0000
	s_mov_b32 s81, 0
	v_writelane_b32 v255, s81, 5
	v_writelane_b32 v253, s13, 40
	s_add_u32 s12, s86, 0x4800000
	s_addc_u32 s13, s87, 0
	v_writelane_b32 v253, s12, 41
	s_mov_b32 s91, 0
	s_mov_b64 s[92:93], 0x80
	v_writelane_b32 v253, s13, 42
	s_add_u32 s12, s86, 0x58f0000
	s_addc_u32 s13, s87, 0
	v_writelane_b32 v253, s12, 43
	s_add_u32 s1, s86, 0x76f0000
	s_nop 0
	v_writelane_b32 v253, s13, 44
	v_writelane_b32 v253, s1, 45
	s_addc_u32 s1, s87, 0
	v_writelane_b32 v253, s1, 46
	s_add_u32 s1, s6, 0xa400000
	v_writelane_b32 v253, s1, 47
	s_addc_u32 s1, s7, 0
	s_add_u32 s12, s6, 0x12309400
	v_writelane_b32 v253, s1, 48
	s_addc_u32 s13, s7, 0
	v_writelane_b32 v253, s12, 49
	s_sub_i32 s1, s42, 40
	s_nop 0
	v_writelane_b32 v253, s13, 50
	v_writelane_b32 v253, s1, 51
	s_add_u32 s1, s58, 0x400000
	v_writelane_b32 v253, s1, 52
	s_addc_u32 s1, s59, 0
	v_writelane_b32 v253, s1, 53
	s_add_u32 s1, s6, 0x8200000
	v_writelane_b32 v253, s1, 54
	s_addc_u32 s1, s7, 0
	v_writelane_b32 v253, s1, 55
	s_add_u32 s1, s8, 0x2000
	v_writelane_b32 v253, s1, 56
	v_writelane_b32 v253, s8, 57
	s_addc_u32 s1, s9, 0
	s_nop 0
	v_writelane_b32 v253, s9, 58
	v_writelane_b32 v253, s10, 59
	v_writelane_b32 v253, s11, 60
	s_add_u32 s8, s70, 0x200
	v_writelane_b32 v253, s1, 61
	s_addc_u32 s9, s71, 0
	v_writelane_b32 v253, s8, 62
	s_nop 1
	v_writelane_b32 v253, s9, 63
	s_add_u32 s8, s70, 0x1000
	s_addc_u32 s9, s71, 0
	v_writelane_b32 v254, s8, 0
	s_nop 1
	v_writelane_b32 v254, s9, 1
	s_add_u32 s8, s70, 0x1100
	s_addc_u32 s9, s71, 0
	v_writelane_b32 v254, s8, 2
	s_nop 1
	v_writelane_b32 v254, s9, 3
	s_add_u32 s8, s70, 0x1200
	s_addc_u32 s9, s71, 0
	v_writelane_b32 v254, s8, 4
	s_nop 1
	v_writelane_b32 v254, s9, 5
	s_add_u32 s8, s70, 0x1300
	s_addc_u32 s9, s71, 0
	v_writelane_b32 v254, s8, 6
	s_nop 1
	v_writelane_b32 v254, s9, 7
	s_add_u32 s8, s70, 0x3400
	s_addc_u32 s9, s71, 0
	v_writelane_b32 v254, s8, 8
	s_nop 1
	v_writelane_b32 v254, s9, 9
	s_add_u32 s8, s70, 0x3500
	s_addc_u32 s9, s71, 0
	v_writelane_b32 v254, s8, 10
	s_cmp_eq_u32 s43, 7
	s_mov_b32 s43, s0
	v_writelane_b32 v254, s9, 11
	s_cselect_b64 s[0:1], -1, 0
	v_writelane_b32 v254, s0, 12
	s_lshl_b32 s8, s42, 5
	s_nop 0
	v_writelane_b32 v254, s1, 13
	s_abs_i32 s0, s42
	v_cvt_f32_u32_e32 v1, s0
	v_writelane_b32 v254, s0, 14
	s_sub_i32 s0, 0, s0
	v_rcp_iflag_f32_e32 v1, v1
	s_nop 0
	v_mul_f32_e32 v1, 0x4f7ffffe, v1
	v_cvt_u32_f32_e32 v1, v1
	s_nop 0
	v_readfirstlane_b32 s1, v1
	s_mul_i32 s0, s0, s1
	s_mul_hi_u32 s0, s1, s0
	s_add_i32 s0, s1, s0
	v_lshrrev_b32_e32 v1, 20, v0
	v_lshrrev_b32_e32 v0, 10, v0
	v_writelane_b32 v254, s0, 15
	v_or_b32_e32 v0, v0, v1
	s_movk_i32 s0, 0x3ff
	v_and_or_b32 v0, v0, s0, v191
	s_lshl_b32 s0, s42, 4
	s_lshl_b32 s1, s42, 8
	v_writelane_b32 v254, s0, 16
	s_add_i32 s9, s1, 0xffffb000
	v_writelane_b32 v254, s9, 17
	s_lshl_b32 s9, s42, 9
	v_writelane_b32 v254, s9, 18
	s_lshl_b32 s9, s42, 10
	s_lshl_b32 s0, s42, 3
	v_writelane_b32 v254, s9, 19
	s_add_u32 s10, s6, 0x12426000
	v_writelane_b32 v254, s6, 20
	s_addc_u32 s11, s7, 0
	v_mov_b32_e32 v1, 0
	v_writelane_b32 v254, s7, 21
	v_writelane_b32 v254, s10, 22
	s_mov_b32 s6, s42
	s_nop 0
	v_writelane_b32 v254, s11, 23
	v_writelane_b32 v254, s6, 24
	v_writelane_b32 v254, s0, 25
	s_addk_i32 s0, 0xfec0
	v_writelane_b32 v254, s0, 26
	v_writelane_b32 v254, s1, 27
	s_add_i32 s0, s1, 0xffffd800
	v_writelane_b32 v254, s0, 28
	v_writelane_b32 v254, s8, 29
	s_add_i32 s0, s8, 0xfffffb00
	v_writelane_b32 v254, s0, 30
	s_add_i32 s0, 0, 0x10400
	v_writelane_b32 v254, s0, 31
	s_add_i32 s0, 0, 0x23ff0
	v_writelane_b32 v254, s0, 32
	s_add_i32 s0, 0, 0x23ff4
	v_writelane_b32 v254, s0, 33
	v_cmp_eq_u32_e64 s[0:1], 0, v0
	s_nop 1
	v_writelane_b32 v254, s0, 34
	s_nop 1
	v_writelane_b32 v254, s1, 35
	v_writelane_b32 v254, s43, 36
	v_writelane_b32 v254, s60, 37
	v_writelane_b32 v254, s41, 38
	v_writelane_b32 v254, s40, 39
	v_writelane_b32 v254, s88, 40
	s_nop 1
	v_writelane_b32 v254, s89, 41
	v_writelane_b32 v254, s84, 42
	s_nop 1
	v_writelane_b32 v254, s85, 43
	v_writelane_b32 v254, s86, 44
	v_writelane_b32 v254, s87, 45
	s_branch .LBB0_9

; __device__ __forceinline__ float bf_lo(unsigned u) { return __uint_as_float(u << 16); }
; __device__ __forceinline__ float bf_hi(unsigned u) { return __uint_as_float(u & 0xffff0000u); }
;     __device__ __forceinline__ bool operator()(f32x4 (&acc)[2][2][4][2], const Unit& un, int wr, int wc, int fr, int fq) const {
;     ...
;                 for (int m = 0; m < 2; ++m)
; #pragma unroll
;                     for (int bj = 0; bj < 2; ++bj) {
;                         const u32x4 a = gp[m][bj], b = gr[m][bj];
;                         f32x4& v0 = acc[ai][bj][mh * 2 + m][0]; f32x4& v1 = acc[ai][bj][mh * 2 + m][1];
;                         if (mode == 0) {
;                             v0[0] *= bf_lo(a.x) * __builtin_amdgcn_rcpf(bf_lo(b.x)); v0[1] *= bf_hi(a.x) * __builtin_amdgcn_rcpf(bf_hi(b.x));
;                             v0[2] *= bf_lo(a.y) * __builtin_amdgcn_rcpf(bf_lo(b.y)); v0[3] *= bf_hi(a.y) * __builtin_amdgcn_rcpf(bf_hi(b.y));
;                             v1[0] *= bf_lo(a.z) * __builtin_amdgcn_rcpf(bf_lo(b.z)); v1[1] *= bf_hi(a.z) * __builtin_amdgcn_rcpf(bf_hi(b.z));
;                             v1[2] *= bf_lo(a.w) * __builtin_amdgcn_rcpf(bf_lo(b.w)); v1[3] *= bf_hi(a.w) * __builtin_amdgcn_rcpf(bf_hi(b.w));
;                         } else {
;                             v0[0] *= bf_lo(a.x); v0[1] *= bf_hi(a.x); v0[2] *= bf_lo(a.y); v0[3] *= bf_hi(a.y);
;                             v1[0] *= bf_lo(a.z); v1[1] *= bf_hi(a.z); v1[2] *= bf_lo(a.w); v1[3] *= bf_hi(a.w);
;                         }
;                     }
;             }
;             if (mode == 0) return true;
; #pragma unroll
;             for (int ai = 0; ai < 2; ++ai)
; #pragma unroll
;                 for (int bj = 0; bj < 2; ++bj)
; #pragma unroll
;                     for (int m = 0; m < 4; ++m)
; #pragma unroll
;                         for (int n = 0; n < 2; ++n)
; #pragma unroll
;                             for (int e = 0; e < 4; ++e) __hip_atomic_store(m1w + (((((ai * 2 + bj) * 4 + m) * 2 + n) * 4 + e) * 64), acc[ai][bj][m][n][e], __ATOMIC_RELAXED, __HIP_MEMORY_SCOPE_AGENT);
.LBB0_251:
	v_pk_mul_f32 v[34:35], v[34:35], v[170:171]
	v_pk_mul_f32 v[32:33], v[32:33], v[168:169]
	v_mul_f32_e32 v99, v99, v165
	v_pk_mul_f32 v[46:47], v[46:47], v[116:117]
	v_pk_mul_f32 v[44:45], v[44:45], v[112:113]
	v_mul_f32_e32 v95, v95, v114
	v_mul_f32_e32 v163, v115, v163
	v_pk_mul_f32 v[42:43], v[42:43], v[228:229]
	v_pk_mul_f32 v[40:41], v[40:41], v[226:227]
	v_mul_f32_e32 v91, v91, v235
	v_pk_mul_f32 v[30:31], v[30:31], v[224:225]
	v_pk_mul_f32 v[28:29], v[28:29], v[222:223]
	v_mul_f32_e32 v87, v87, v252
	v_pk_mul_f32 v[38:39], v[38:39], v[220:221]
	v_pk_mul_f32 v[36:37], v[36:37], v[108:109]
	v_mul_f32_e32 v83, v83, v110
	v_mul_f32_e32 v155, v111, v155
	v_pk_mul_f32 v[26:27], v[26:27], v[218:219]
	v_pk_mul_f32 v[24:25], v[24:25], v[216:217]
	v_mul_f32_e32 v79, v79, v251
	v_pk_mul_f32 v[10:11], v[10:11], v[214:215]
	v_pk_mul_f32 v[8:9], v[8:9], v[212:213]
	v_mul_f32_e32 v75, v75, v250
	v_pk_mul_f32 v[22:23], v[22:23], v[208:209]
	v_pk_mul_f32 v[20:21], v[20:21], v[104:105]
	v_mul_f32_e32 v71, v71, v106
	v_mul_f32_e32 v143, v107, v143
	v_pk_mul_f32 v[18:19], v[18:19], v[206:207]
	v_pk_mul_f32 v[16:17], v[16:17], v[204:205]
	v_mul_f32_e32 v67, v67, v249
	v_pk_mul_f32 v[6:7], v[6:7], v[202:203]
	v_pk_mul_f32 v[4:5], v[4:5], v[200:201]
	v_mul_f32_e32 v63, v63, v131
	v_pk_mul_f32 v[14:15], v[14:15], v[198:199]
	v_pk_mul_f32 v[12:13], v[12:13], v[100:101]
	v_mul_f32_e32 v59, v59, v102
	v_mul_f32_e32 v131, v103, v0
	v_pk_mul_f32 v[50:51], v[50:51], v[144:145]
	v_pk_mul_f32 v[48:49], v[48:49], v[118:119]
	v_mul_f32_e32 v55, v55, v133
	s_and_b64 vcc, exec, s[0:1]
	s_cbranch_vccz .LBB0_256
	s_movk_i32 s0, 0x1000
	v_add_co_u32_e32 v100, vcc, s0, v2
	s_movk_i32 s0, 0x2000
	s_nop 0
	v_addc_co_u32_e32 v101, vcc, 0, v3, vcc
	v_add_co_u32_e32 v102, vcc, s0, v2
	s_movk_i32 s0, 0x3000
	s_nop 0
	v_addc_co_u32_e32 v103, vcc, 0, v3, vcc
	global_store_dword v[2:3], v124, off sc1
	global_store_dword v[2:3], v125, off offset:256 sc1
	global_store_dword v[2:3], v126, off offset:512 sc1
	global_store_dword v[2:3], v127, off offset:768 sc1
	global_store_dword v[2:3], v128, off offset:1024 sc1
	global_store_dword v[2:3], v129, off offset:1280 sc1
	global_store_dword v[2:3], v130, off offset:1536 sc1
	global_store_dword v[2:3], v131, off offset:1792 sc1
	global_store_dword v[2:3], v4, off offset:2048 sc1
	global_store_dword v[2:3], v5, off offset:2304 sc1
	global_store_dword v[2:3], v6, off offset:2560 sc1
	global_store_dword v[2:3], v7, off offset:2816 sc1
	global_store_dword v[2:3], v60, off offset:3072 sc1
	global_store_dword v[2:3], v61, off offset:3328 sc1
	global_store_dword v[2:3], v62, off offset:3584 sc1
	global_store_dword v[2:3], v63, off offset:3840 sc1
	global_store_dword v[102:103], v136, off offset:-4096 sc1
	global_store_dword v[100:101], v137, off offset:256 sc1
	global_store_dword v[100:101], v138, off offset:512 sc1
	global_store_dword v[100:101], v139, off offset:768 sc1
	global_store_dword v[100:101], v140, off offset:1024 sc1
	global_store_dword v[100:101], v141, off offset:1280 sc1
	global_store_dword v[100:101], v142, off offset:1536 sc1
	global_store_dword v[100:101], v143, off offset:1792 sc1
	global_store_dword v[100:101], v8, off offset:2048 sc1
	global_store_dword v[100:101], v9, off offset:2304 sc1
	global_store_dword v[100:101], v10, off offset:2560 sc1
	global_store_dword v[100:101], v11, off offset:2816 sc1
	global_store_dword v[100:101], v72, off offset:3072 sc1
	global_store_dword v[100:101], v73, off offset:3328 sc1
	global_store_dword v[100:101], v74, off offset:3584 sc1
	global_store_dword v[100:101], v75, off offset:3840 sc1
	global_store_dword v[102:103], v12, off sc1
	global_store_dword v[102:103], v13, off offset:256 sc1
	global_store_dword v[102:103], v14, off offset:512 sc1
	global_store_dword v[102:103], v15, off offset:768 sc1
	global_store_dword v[102:103], v56, off offset:1024 sc1
	global_store_dword v[102:103], v57, off offset:1280 sc1
	global_store_dword v[102:103], v58, off offset:1536 sc1
	global_store_dword v[102:103], v59, off offset:1792 sc1
	global_store_dword v[102:103], v16, off offset:2048 sc1
	global_store_dword v[102:103], v17, off offset:2304 sc1
	global_store_dword v[102:103], v18, off offset:2560 sc1
	global_store_dword v[102:103], v19, off offset:2816 sc1
	global_store_dword v[102:103], v64, off offset:3072 sc1
	global_store_dword v[102:103], v65, off offset:3328 sc1
	global_store_dword v[102:103], v66, off offset:3584 sc1
	global_store_dword v[102:103], v67, off offset:3840 sc1
	v_add_co_u32_e32 v100, vcc, s0, v2
	s_movk_i32 s0, 0x4000
	s_nop 0
	v_addc_co_u32_e32 v101, vcc, 0, v3, vcc
	v_add_co_u32_e32 v102, vcc, s0, v2
	s_movk_i32 s0, 0x5000
	s_nop 0
	v_addc_co_u32_e32 v103, vcc, 0, v3, vcc
	global_store_dword v[102:103], v20, off offset:-4096 sc1
	global_store_dword v[100:101], v21, off offset:256 sc1
	global_store_dword v[100:101], v22, off offset:512 sc1
	global_store_dword v[100:101], v23, off offset:768 sc1
;     __device__ __forceinline__ bool operator()(f32x4 (&acc)[2][2][4][2], const Unit& un, int wr, int wc, int fr, int fq) const {
;     ...
;                             for (int e = 0; e < 4; ++e) __hip_atomic_store(m1w + (((((ai * 2 + bj) * 4 + m) * 2 + n) * 4 + e) * 64), acc[ai][bj][m][n][e], __ATOMIC_RELAXED, __HIP_MEMORY_SCOPE_AGENT);
;             asm volatile("s_waitcnt vmcnt(0)" ::: "memory");
;             __builtin_amdgcn_fence(__ATOMIC_RELEASE, "agent");
;             asm volatile("s_waitcnt vmcnt(0)" ::: "memory");
;             if (fr == 0 && fq == 0) __hip_atomic_fetch_add(flag, 1u, __ATOMIC_RELAXED, __HIP_MEMORY_SCOPE_AGENT);
	global_store_dword v[100:101], v68, off offset:1024 sc1
	global_store_dword v[100:101], v69, off offset:1280 sc1
	global_store_dword v[100:101], v70, off offset:1536 sc1
	global_store_dword v[100:101], v71, off offset:1792 sc1
	global_store_dword v[100:101], v24, off offset:2048 sc1
	global_store_dword v[100:101], v25, off offset:2304 sc1
	global_store_dword v[100:101], v26, off offset:2560 sc1
	global_store_dword v[100:101], v27, off offset:2816 sc1
	global_store_dword v[100:101], v76, off offset:3072 sc1
	global_store_dword v[100:101], v77, off offset:3328 sc1
	global_store_dword v[100:101], v78, off offset:3584 sc1
	global_store_dword v[100:101], v79, off offset:3840 sc1
	global_store_dword v[102:103], v148, off sc1
	global_store_dword v[102:103], v149, off offset:256 sc1
	global_store_dword v[102:103], v150, off offset:512 sc1
	global_store_dword v[102:103], v151, off offset:768 sc1
	global_store_dword v[102:103], v152, off offset:1024 sc1
	global_store_dword v[102:103], v153, off offset:1280 sc1
	global_store_dword v[102:103], v154, off offset:1536 sc1
	global_store_dword v[102:103], v155, off offset:1792 sc1
	global_store_dword v[102:103], v28, off offset:2048 sc1
	global_store_dword v[102:103], v29, off offset:2304 sc1
	global_store_dword v[102:103], v30, off offset:2560 sc1
	global_store_dword v[102:103], v31, off offset:2816 sc1
	global_store_dword v[102:103], v84, off offset:3072 sc1
	global_store_dword v[102:103], v85, off offset:3328 sc1
	global_store_dword v[102:103], v86, off offset:3584 sc1
	global_store_dword v[102:103], v87, off offset:3840 sc1
	v_add_co_u32_e32 v100, vcc, s0, v2
	s_movk_i32 s0, 0x6000
	s_nop 0
	v_addc_co_u32_e32 v101, vcc, 0, v3, vcc
	v_add_co_u32_e32 v102, vcc, s0, v2
	s_nop 1
	v_addc_co_u32_e32 v103, vcc, 0, v3, vcc
	v_add_co_u32_e32 v2, vcc, s74, v2
	global_store_dword v[102:103], v156, off offset:-4096 sc1
	global_store_dword v[100:101], v157, off offset:256 sc1
	global_store_dword v[100:101], v158, off offset:512 sc1
	global_store_dword v[100:101], v159, off offset:768 sc1
	global_store_dword v[100:101], v160, off offset:1024 sc1
	global_store_dword v[100:101], v161, off offset:1280 sc1
	global_store_dword v[100:101], v162, off offset:1536 sc1
	global_store_dword v[100:101], v163, off offset:1792 sc1
	global_store_dword v[100:101], v32, off offset:2048 sc1
	global_store_dword v[100:101], v33, off offset:2304 sc1
	global_store_dword v[100:101], v34, off offset:2560 sc1
	global_store_dword v[100:101], v35, off offset:2816 sc1
	global_store_dword v[100:101], v96, off offset:3072 sc1
	global_store_dword v[100:101], v97, off offset:3328 sc1
	global_store_dword v[100:101], v98, off offset:3584 sc1
	global_store_dword v[100:101], v99, off offset:3840 sc1
	global_store_dword v[102:103], v36, off sc1
	global_store_dword v[102:103], v37, off offset:256 sc1
	global_store_dword v[102:103], v38, off offset:512 sc1
	global_store_dword v[102:103], v39, off offset:768 sc1
	global_store_dword v[102:103], v80, off offset:1024 sc1
	global_store_dword v[102:103], v81, off offset:1280 sc1
	global_store_dword v[102:103], v82, off offset:1536 sc1
	global_store_dword v[102:103], v83, off offset:1792 sc1
	global_store_dword v[102:103], v40, off offset:2048 sc1
	global_store_dword v[102:103], v41, off offset:2304 sc1
	global_store_dword v[102:103], v42, off offset:2560 sc1
	global_store_dword v[102:103], v43, off offset:2816 sc1
	global_store_dword v[102:103], v88, off offset:3072 sc1
	global_store_dword v[102:103], v89, off offset:3328 sc1
	global_store_dword v[102:103], v90, off offset:3584 sc1
	global_store_dword v[102:103], v91, off offset:3840 sc1
	v_addc_co_u32_e32 v3, vcc, 0, v3, vcc
	global_store_dword v[2:3], v44, off sc1
	global_store_dword v[2:3], v45, off offset:256 sc1
	global_store_dword v[2:3], v46, off offset:512 sc1
	global_store_dword v[2:3], v47, off offset:768 sc1
	global_store_dword v[2:3], v92, off offset:1024 sc1
	global_store_dword v[2:3], v93, off offset:1280 sc1
	global_store_dword v[2:3], v94, off offset:1536 sc1
	global_store_dword v[2:3], v95, off offset:1792 sc1
	global_store_dword v[2:3], v48, off offset:2048 sc1
	global_store_dword v[2:3], v49, off offset:2304 sc1
	global_store_dword v[2:3], v50, off offset:2560 sc1
	global_store_dword v[2:3], v51, off offset:2816 sc1
	global_store_dword v[2:3], v52, off offset:3072 sc1
	global_store_dword v[2:3], v53, off offset:3328 sc1
	global_store_dword v[2:3], v54, off offset:3584 sc1
	global_store_dword v[2:3], v55, off offset:3840 sc1
	s_waitcnt vmcnt(0)
	s_waitcnt vmcnt(0) lgkmcnt(0)
	s_waitcnt vmcnt(0)
	s_and_saveexec_b64 s[0:1], s[6:7]
	s_cbranch_execz .LBB0_255
	s_mov_b64 s[10:11], exec
	v_mbcnt_lo_u32_b32 v0, s10, 0
	v_mbcnt_hi_u32_b32 v0, s11, v0
	v_cmp_eq_u32_e32 vcc, 0, v0
	s_and_b64 s[24:25], exec, vcc
	s_mov_b64 exec, s[24:25]
	s_cbranch_execz .LBB0_255
	s_bcnt1_i32_b64 s9, s[10:11]
	v_mov_b32_e32 v0, s9
	global_atomic_add v1, v0, s[14:15]

; __device__ void phase0(const Params& p, LAS unsigned char* lds, const int tid_in, const int bid) {
;     ...
;     for (int it = bid; it < NT_L + NROWI; it += gridDim.x) {
;         if (it < NT_L) {
;             conv_item(p, 0, it, lds, tid);
; __device__ __forceinline__ void run_phase(const Params& p, int ph, LAS unsigned char* lds, const int tid, const int bid) {
;     ...
;         SchedPlain S; S.init(MPAD, NIN, G, bid); S.A = pws(p) + OFF_XB; S.Bt = pws(p) + OFF_WIN + l * SZ_WIN; S.tstepA = (size_t)256 * D * 2; S.tstepB = (size_t)256 * D * 2;
;         EpiWin E; E.u = (float*)(pws(p) + OFF_U); E.zb = (bf16_t*)(pws(p) + OFF_ZB); E.rsq = (const float*)(pws(p) + OFF_RSQ) + (size_t)l * MPAD; E.cf = (const float*)(pws(p) + OFF_CS);
;         gemm_phase(lds, S, E, D, D, D, tid); }
.LBB0_581:
	s_barrier
	s_cmp_eq_u32 s81, 1
	s_cbranch_scc0 .LBB0_582
	s_cmpk_lg_u32 s42, 0x100
	s_cbranch_scc1 .LBB0_582
	s_cmpk_lt_u32 s82, 0x40
	s_cbranch_scc1 .LBB0_582
	s_mov_b32 s0, 1
	s_nop 0
	v_writelane_b32 v255, s0, 5
	s_addk_i32 s82, 0x7c0
	s_branch .Lp0_pre

; #define LAS __attribute__((address_space(3)))
; __device__ __forceinline__ void tr_tile(LAS float* tile, const float* src, int N, bf16_t* dst, int Kd, int k0, int n0, const float* scale, const float* nscale, int tid) {
;     constexpr int P = 257;
;     f32x4 v[8];
; #pragma unroll
;     for (int i = 0; i < 8; ++i) { const int idx4 = i * 512 + tid, r = idx4 >> 6, c4 = (idx4 & 63) * 4;
;         v[i] = __builtin_nontemporal_load((const f32x4*)(src + (size_t)(k0 + r) * N + n0 + c4)); }
; #pragma unroll
;     for (int i = 0; i < 8; ++i) { const int idx4 = i * 512 + tid, r = idx4 >> 6, c4 = (idx4 & 63) * 4;
;         f32x4 w = v[i]; if (scale) w *= scale[k0 + r]; if (nscale) w *= *(const f32x4*)(nscale + n0 + c4);
;         tile[r * P + c4] = w[0]; tile[r * P + c4 + 1] = w[1]; tile[r * P + c4 + 2] = w[2]; tile[r * P + c4 + 3] = w[3]; }
;     __syncthreads();
; #pragma unroll
;     for (int i = 0; i < 8; ++i) { const int idx = i * 512 + tid, n = idx >> 4, k4 = (idx & 15) * 4;
;         u32x2 w; w.x = pk_bf16(tile[(k4) * P + n], tile[(k4 + 1) * P + n]); w.y = pk_bf16(tile[(k4 + 2) * P + n], tile[(k4 + 3) * P + n]);
;         *(u32x2*)(dst + (size_t)(n0 + n) * Kd + k0 + k4) = w; }
;     __syncthreads();
; }
; __device__ __forceinline__ void conv_item(const Params& p, int l, int t, LAS unsigned char* lds, int tid) {
;     LAS float* tile = (LAS float*)lds;
;     if (t < 2048) { const int kt = t >> 6, nt_ = t & 63;
;         tr_tile(tile, p.w_in + (size_t)l * D * NIN, NIN, (bf16_t*)(pws(p) + OFF_WIN + l * SZ_WIN), D, kt * 64, nt_ * 256, p.norm_gain + l * D, nullptr, tid);
;     } else if (t < 2112) { const int g = (t - 2048) >> 4, tt = (t - 2048) & 15, kt = tt >> 1, nt_ = tt & 1;
;         tr_tile(tile, p.pool_w + ((size_t)l * 4 + g) * 512 * 512, 512, (bf16_t*)(pws(p) + OFF_WPOOL + l * SZ_WPOOL) + (size_t)g * 512 * 512, 512, kt * 64, nt_ * 256, nullptr, p.pool_scale + (size_t)l * D + g * 512, tid);
;     } else { const int j = (t - 2112) >> 8, tt = (t - 2112) & 255, kt = tt >> 3, nt_ = tt & 7;
;         const float* src = (j == 0 ? p.proj_pool : j == 1 ? p.proj_ret : p.w_out) + (size_t)l * D * D;
; __device__ void phase0(const Params& p, LAS unsigned char* lds, const int tid_in, const int bid) {
;     ...
;     for (int it = bid; it < NT_L + NROWI; it += gridDim.x) {
;         if (it < NT_L) {
;             conv_item(p, 0, it, lds, tid);
.Lp0_pre:
	s_waitcnt vmcnt(0)
	v_lshlrev_b32_e32 v2, 2, v244
	v_add_u32_e32 v4, 0x200, v244
	v_add_u32_e32 v5, 0x400, v244
	v_add_u32_e32 v6, 0x600, v244
	v_add_u32_e32 v7, 0x800, v244
	v_add_u32_e32 v8, 0xa00, v244
	v_add_u32_e32 v9, 0xc00, v244
	v_add_u32_e32 v10, 0xe00, v244
	v_ashrrev_i32_e32 v39, 6, v244
	v_and_b32_e32 v40, 0xfc, v2
	v_ashrrev_i32_e32 v43, 6, v4
	v_ashrrev_i32_e32 v74, 6, v5
	v_ashrrev_i32_e32 v75, 6, v6
	v_ashrrev_i32_e32 v76, 6, v7
	v_ashrrev_i32_e32 v77, 6, v8
	v_ashrrev_i32_e32 v78, 6, v9
	v_ashrrev_i32_e32 v79, 6, v10
	s_movk_i32 s0, 0x404
	v_and_b32_e32 v42, 60, v2
	v_and_b32_e32 v3, 63, v244
	v_lshlrev_b32_e32 v0, 2, v40
	v_mul_lo_u32 v81, v39, s0
	v_mul_lo_u32 v82, v43, s0
	v_mul_lo_u32 v83, v74, s0
	v_mul_lo_u32 v84, v75, s0
	v_mul_lo_u32 v85, v76, s0
	v_mul_lo_u32 v86, v77, s0
	v_mul_lo_u32 v87, v78, s0
	v_mul_lo_u32 v88, v79, s0
	v_mad_u32_u24 v2, v42, s0, 0
	v_readlane_b32 s0, v254, 20
	v_lshlrev_b32_e32 v38, 2, v3
	v_add_u32_e32 v80, 0, v0
	v_ashrrev_i32_e32 v89, 4, v244
	v_ashrrev_i32_e32 v91, 4, v4
	v_ashrrev_i32_e32 v93, 4, v5
	v_ashrrev_i32_e32 v95, 4, v6
	v_ashrrev_i32_e32 v97, 4, v7
	v_ashrrev_i32_e32 v99, 4, v8
	v_ashrrev_i32_e32 v101, 4, v9
	v_ashrrev_i32_e32 v103, 4, v10
	v_lshl_add_u64 v[44:45], s[56:57], 0, v[0:1]
	v_lshlrev_b32_e32 v0, 1, v42
	v_readlane_b32 s1, v254, 21
	v_lshl_add_u32 v90, v89, 2, v2
	v_lshl_add_u32 v92, v91, 2, v2
	v_lshl_add_u32 v94, v93, 2, v2
	v_lshl_add_u32 v96, v95, 2, v2
	v_lshl_add_u32 v98, v97, 2, v2
	v_lshl_add_u32 v100, v99, 2, v2
	v_lshl_add_u32 v102, v101, 2, v2
	v_lshl_add_u32 v104, v103, 2, v2
	v_or_b32_e32 v2, 0x400, v38
	v_or_b32_e32 v4, 0x500, v38
	v_or_b32_e32 v6, 0x600, v38
	v_or_b32_e32 v8, 0x700, v38
	v_lshl_add_u64 v[46:47], s[0:1], 0, v[0:1]
	v_lshlrev_b32_e32 v0, 3, v3
	v_add_u32_e32 v41, 0xffffa600, v39
	v_cmp_eq_u32_e64 s[6:7], 0, v3
	v_lshl_add_u64 v[48:49], s[68:69], 0, v[0:1]
	v_readlane_b32 s0, v255, 5
	s_nop 0
	s_cmp_lg_u32 s0, 0
	s_cbranch_scc1 .Lp0_fwd0
	s_cmpk_lg_u32 s42, 0x100
	s_cbranch_scc1 .Lp0_fwd0
	s_bitcmp1_b32 s82, 3
	s_cbranch_scc0 .Lp0_fwd0
	s_sub_i32 s0, 0xfdf, s82
	s_andn2_b32 s0, s0, 0xff
	s_add_i32 s82, s82, s0

; __device__ void phase0(const Params& p, LAS unsigned char* lds, const int tid_in, const int bid) {
;     ...
;     for (int it = bid; it < NT_L + NROWI; it += gridDim.x) {
;         if (it < NT_L) {
;             conv_item(p, 0, it, lds, tid);
.LBB0_590:
	v_readlane_b32 s0, v255, 5
	s_nop 0
	s_cmp_lg_u32 s0, 0
	s_cbranch_scc0 .Lp0_notail
	s_addk_i32 s82, 0xc0
	s_addk_i32 s12, 0x600
	s_add_i32 s13, s13, 0xc000
	s_addk_i32 s14, 0x1800
	s_cmpk_lt_u32 s82, 0xb40
	s_cbranch_scc1 .LBB0_591
	s_mov_b32 s0, 0
	s_nop 0
	v_writelane_b32 v255, s0, 5
	s_branch .LBB0_660
.Lp0_notail:
	s_cmpk_lg_u32 s42, 0x100
	s_cbranch_scc1 .Lp0_fwd1
	s_bitcmp1_b32 s82, 3
	s_cbranch_scc0 .Lp0_fwd1
	v_readlane_b32 s0, v254, 25
	s_nop 0
	s_sub_i32 s12, s12, s0
	v_readlane_b32 s0, v254, 27
	s_nop 0
	s_sub_i32 s13, s13, s0
	v_readlane_b32 s0, v254, 29
	s_nop 0
	s_sub_i32 s14, s14, s0
	s_sub_i32 s82, s82, s42
	s_cmpk_lt_i32 s82, 0x800
	s_cbranch_scc1 .Lp0_noskipr
	s_cmpk_gt_i32 s82, 0xb3f
	s_cbranch_scc1 .Lp0_noskipr
	s_addk_i32 s82, 0xfcc0
	s_addk_i32 s12, 0xe600
	s_add_i32 s13, s13, 0xfffcc000
	s_addk_i32 s14, 0x9800
.Lp0_noskipr:
	s_cmp_lt_i32 s82, 0
	s_cbranch_scc1 .LBB0_660
	s_branch .LBB0_591
.Lp0_fwd1:
	v_readlane_b32 s0, v254, 25
	s_add_i32 s12, s12, s0
	v_readlane_b32 s0, v254, 27
	s_add_i32 s13, s13, s0
	v_readlane_b32 s0, v254, 29
	s_add_i32 s82, s82, s42
	s_add_i32 s14, s14, s0
	s_cmpk_lg_u32 s42, 0x100
	s_cbranch_scc1 .Lp0_noskipf
	s_cmpk_lt_i32 s82, 0x800
	s_cbranch_scc1 .Lp0_noskipf
	s_cmpk_gt_i32 s82, 0xb3f
	s_cbranch_scc1 .Lp0_noskipf
	s_addk_i32 s82, 0x340
	s_addk_i32 s12, 0x1a00
	s_add_i32 s13, s13, 0x34000
	s_addk_i32 s14, 0x6800
.Lp0_noskipf:
	s_cmpk_gt_i32 s82, 0xfdf
	s_cbranch_scc1 .LBB0_660
